# K-loop: removed 8 redundant post-barrier lgkmcnt(0) and merged vmcnt(8)+lgkmcnt(0) waits into one instruction per phase
# baseline (speedup 1.0000x reference)
.LBB0_293:
	v_readlane_b32 s0, v255, 31
	v_readlane_b32 s1, v255, 32
	s_andn2_b64 vcc, exec, s[0:1]
	s_cbranch_vccnz .LBB0_296
	s_add_u32 s0, s90, 0x80
	s_addc_u32 s1, s91, 0
	s_add_u32 s11, s2, 0x100
	s_addc_u32 s24, s3, 0
	s_mov_b32 s2, 0
	s_add_i32 s90, s2, 2
	s_add_u32 s82, s0, 0x80
	s_addc_u32 s3, s1, 0
	s_add_i32 s83, 0, 0x10000
	s_cmp_eq_u32 s62, s2
	s_cselect_b32 s3, s23, s3
	s_cselect_b32 s2, s22, s82
	s_cselect_b32 vcc_hi, s13, s24
	s_cselect_b32 vcc_lo, s12, s11
	s_add_i32 s82, 0, 0x14000
	v_add_u32_e32 v140, s83, v157
	v_add_u32_e32 v144, s82, v157
	ds_read_b128 v[128:131], v140
	ds_read_b128 v[132:135], v140 offset:1024
	ds_read_b128 v[136:139], v140 offset:2048
	ds_read_b128 v[140:143], v140 offset:3072
	ds_read_b128 v[166:169], v144
	ds_read_b128 v[176:179], v144 offset:1024
	ds_read_b128 v[180:183], v144 offset:2048
	ds_read_b128 v[184:187], v144 offset:3072
	v_lshl_add_u64 v[170:171], s[0:1], 0, v[160:161]
	s_add_i32 m0, s37, 0xc000
	ds_read_b128 v[188:191], v242
	ds_read_b128 v[192:195], v242 offset:1024
	ds_read_b128 v[196:199], v242 offset:2048
	ds_read_b128 v[200:203], v242 offset:3072
	ds_read_b128 v[204:207], v242 offset:4096
	ds_read_b128 v[208:211], v242 offset:5120
	ds_read_b128 v[212:215], v242 offset:6144
	ds_read_b128 v[216:219], v242 offset:7168
	global_load_lds_dwordx4 v[170:171], off
	v_lshl_add_u64 v[170:171], s[0:1], 0, v[162:163]
	s_add_i32 m0, s37, 0xe000
	s_nop 0
	global_load_lds_dwordx4 v[170:171], off
	s_waitcnt vmcnt(8) lgkmcnt(0)
	s_barrier
	s_setprio 1
	v_mfma_f32_16x16x32_bf16 v[124:127], v[128:131], v[188:191], 0
	v_mfma_f32_16x16x32_bf16 v[120:123], v[136:139], v[188:191], 0
	v_mfma_f32_16x16x32_bf16 v[108:111], v[128:131], v[196:199], 0
	v_mfma_f32_16x16x32_bf16 v[104:107], v[136:139], v[196:199], 0
	v_mfma_f32_16x16x32_bf16 v[92:95], v[128:131], v[204:207], 0
	v_mfma_f32_16x16x32_bf16 v[88:91], v[136:139], v[204:207], 0
	v_mfma_f32_16x16x32_bf16 v[76:79], v[128:131], v[212:215], 0
	v_mfma_f32_16x16x32_bf16 v[72:75], v[136:139], v[212:215], 0
	v_mfma_f32_16x16x32_bf16 v[124:127], v[132:135], v[192:195], v[124:127]
	v_mfma_f32_16x16x32_bf16 v[120:123], v[140:143], v[192:195], v[120:123]
	v_mfma_f32_16x16x32_bf16 v[108:111], v[132:135], v[200:203], v[108:111]
	v_mfma_f32_16x16x32_bf16 v[104:107], v[140:143], v[200:203], v[104:107]
	v_mfma_f32_16x16x32_bf16 v[92:95], v[132:135], v[208:211], v[92:95]
	v_mfma_f32_16x16x32_bf16 v[88:91], v[140:143], v[208:211], v[88:91]
	v_mfma_f32_16x16x32_bf16 v[76:79], v[132:135], v[216:219], v[76:79]
	v_mfma_f32_16x16x32_bf16 v[72:75], v[140:143], v[216:219], v[72:75]
	s_setprio 0
	s_setprio 1
	v_mfma_f32_16x16x32_bf16 v[116:119], v[166:169], v[188:191], 0
	v_mfma_f32_16x16x32_bf16 v[112:115], v[180:183], v[188:191], 0
	v_mfma_f32_16x16x32_bf16 v[100:103], v[166:169], v[196:199], 0
	v_mfma_f32_16x16x32_bf16 v[96:99], v[180:183], v[196:199], 0
	v_mfma_f32_16x16x32_bf16 v[84:87], v[166:169], v[204:207], 0
	v_mfma_f32_16x16x32_bf16 v[80:83], v[180:183], v[204:207], 0
	v_mfma_f32_16x16x32_bf16 v[68:71], v[166:169], v[212:215], 0
	v_mfma_f32_16x16x32_bf16 v[64:67], v[180:183], v[212:215], 0
	v_mfma_f32_16x16x32_bf16 v[116:119], v[176:179], v[192:195], v[116:119]
	v_mfma_f32_16x16x32_bf16 v[112:115], v[184:187], v[192:195], v[112:115]
	v_mfma_f32_16x16x32_bf16 v[100:103], v[176:179], v[200:203], v[100:103]
	v_mfma_f32_16x16x32_bf16 v[96:99], v[184:187], v[200:203], v[96:99]
	v_mfma_f32_16x16x32_bf16 v[84:87], v[176:179], v[208:211], v[84:87]
	v_mfma_f32_16x16x32_bf16 v[80:83], v[184:187], v[208:211], v[80:83]
	v_mfma_f32_16x16x32_bf16 v[68:71], v[176:179], v[216:219], v[68:71]
	v_mfma_f32_16x16x32_bf16 v[64:67], v[184:187], v[216:219], v[64:67]
	s_setprio 0
	s_barrier
	s_add_i32 s83, s83, s36
	v_lshl_add_u64 v[170:171], vcc, 0, v[150:151]
	s_mov_b32 m0, s83
	ds_read_b128 v[188:191], v242 offset:16384
	ds_read_b128 v[192:195], v242 offset:17408
	ds_read_b128 v[196:199], v242 offset:18432
	ds_read_b128 v[200:203], v242 offset:19456
	ds_read_b128 v[204:207], v242 offset:20480
	ds_read_b128 v[208:211], v242 offset:21504
	ds_read_b128 v[212:215], v242 offset:22528
	ds_read_b128 v[216:219], v242 offset:23552
	global_load_lds_dwordx4 v[170:171], off
	s_add_i32 m0, s83, 0x2000
	v_lshl_add_u64 v[232:233], vcc, 0, v[154:155]
	s_add_u32 vcc_lo, vcc_lo, s26
	s_addc_u32 vcc_hi, vcc_hi, 0
	s_add_i32 s82, s82, s36
	global_load_lds_dwordx4 v[232:233], off
	v_lshl_add_u64 v[234:235], vcc, 0, v[150:151]
	s_mov_b32 m0, s82
	v_lshl_add_u64 v[246:247], vcc, 0, v[154:155]
	global_load_lds_dwordx4 v[234:235], off
	s_add_i32 m0, s82, 0x2000
	v_lshl_add_u64 v[248:249], s[2:3], 0, v[148:149]
	global_load_lds_dwordx4 v[246:247], off
	s_mov_b32 m0, s37
	v_lshl_add_u64 v[250:251], s[2:3], 0, v[152:153]
	global_load_lds_dwordx4 v[248:249], off
	s_mov_b32 m0, s42
	s_nop 0
	global_load_lds_dwordx4 v[250:251], off
	s_waitcnt vmcnt(8) lgkmcnt(0)
	s_barrier
	s_setprio 1
	v_mfma_f32_16x16x32_bf16 v[60:63], v[128:131], v[188:191], 0
	v_mfma_f32_16x16x32_bf16 v[56:59], v[136:139], v[188:191], 0
	v_mfma_f32_16x16x32_bf16 v[44:47], v[128:131], v[196:199], 0
	v_mfma_f32_16x16x32_bf16 v[40:43], v[136:139], v[196:199], 0
	v_mfma_f32_16x16x32_bf16 v[28:31], v[128:131], v[204:207], 0
	v_mfma_f32_16x16x32_bf16 v[24:27], v[136:139], v[204:207], 0
	v_mfma_f32_16x16x32_bf16 v[12:15], v[128:131], v[212:215], 0
	v_mfma_f32_16x16x32_bf16 v[8:11], v[136:139], v[212:215], 0
	v_mfma_f32_16x16x32_bf16 v[60:63], v[132:135], v[192:195], v[60:63]
	v_mfma_f32_16x16x32_bf16 v[56:59], v[140:143], v[192:195], v[56:59]
	v_mfma_f32_16x16x32_bf16 v[44:47], v[132:135], v[200:203], v[44:47]
	v_mfma_f32_16x16x32_bf16 v[40:43], v[140:143], v[200:203], v[40:43]
	v_mfma_f32_16x16x32_bf16 v[28:31], v[132:135], v[208:211], v[28:31]
	v_mfma_f32_16x16x32_bf16 v[24:27], v[140:143], v[208:211], v[24:27]
	v_mfma_f32_16x16x32_bf16 v[12:15], v[132:135], v[216:219], v[12:15]
	v_mfma_f32_16x16x32_bf16 v[8:11], v[140:143], v[216:219], v[8:11]
	s_setprio 0
	s_setprio 1
	v_mfma_f32_16x16x32_bf16 v[52:55], v[166:169], v[188:191], 0
	v_mfma_f32_16x16x32_bf16 v[48:51], v[180:183], v[188:191], 0
	v_mfma_f32_16x16x32_bf16 v[36:39], v[166:169], v[196:199], 0
	v_mfma_f32_16x16x32_bf16 v[32:35], v[180:183], v[196:199], 0
	v_mfma_f32_16x16x32_bf16 v[20:23], v[166:169], v[204:207], 0
	v_mfma_f32_16x16x32_bf16 v[16:19], v[180:183], v[204:207], 0
	v_mfma_f32_16x16x32_bf16 v[4:7], v[166:169], v[212:215], 0
	v_mfma_f32_16x16x32_bf16 v[0:3], v[180:183], v[212:215], 0
	v_mfma_f32_16x16x32_bf16 v[52:55], v[176:179], v[192:195], v[52:55]
	v_mfma_f32_16x16x32_bf16 v[48:51], v[184:187], v[192:195], v[48:51]
	v_mfma_f32_16x16x32_bf16 v[36:39], v[176:179], v[200:203], v[36:39]
	v_mfma_f32_16x16x32_bf16 v[32:35], v[184:187], v[200:203], v[32:35]
	v_mfma_f32_16x16x32_bf16 v[20:23], v[176:179], v[208:211], v[20:23]
	v_mfma_f32_16x16x32_bf16 v[16:19], v[184:187], v[208:211], v[16:19]
	v_mfma_f32_16x16x32_bf16 v[4:7], v[176:179], v[216:219], v[4:7]
	v_mfma_f32_16x16x32_bf16 v[0:3], v[184:187], v[216:219], v[0:3]
	s_setprio 0
	s_barrier
	s_add_i32 s82, 0, 0x18000
	s_add_i32 s83, 0, 0x1c000
	v_add_u32_e32 v140, s82, v157
	v_add_u32_e32 v144, s83, v157
	ds_read_b128 v[128:131], v140
	ds_read_b128 v[132:135], v140 offset:1024
	ds_read_b128 v[136:139], v140 offset:2048
	ds_read_b128 v[140:143], v140 offset:3072
	ds_read_b128 v[166:169], v144
	ds_read_b128 v[176:179], v144 offset:1024
	ds_read_b128 v[180:183], v144 offset:2048
	ds_read_b128 v[184:187], v144 offset:3072
	s_add_u32 s2, s2, s58
	s_addc_u32 s3, s3, 0
	s_mov_b32 m0, s43
	v_lshl_add_u64 v[238:239], s[2:3], 0, v[148:149]
	ds_read_b128 v[188:191], v242 offset:32768
	ds_read_b128 v[192:195], v242 offset:33792
	ds_read_b128 v[196:199], v242 offset:34816
	ds_read_b128 v[200:203], v242 offset:35840
	ds_read_b128 v[204:207], v242 offset:36864
	ds_read_b128 v[208:211], v242 offset:37888
	ds_read_b128 v[212:215], v242 offset:38912
	ds_read_b128 v[216:219], v242 offset:39936
	global_load_lds_dwordx4 v[238:239], off
	v_lshl_add_u64 v[238:239], s[2:3], 0, v[152:153]
	s_mov_b32 m0, s16
	s_nop 0
	global_load_lds_dwordx4 v[238:239], off
	s_waitcnt vmcnt(8) lgkmcnt(0)
	s_barrier
	s_setprio 1
	v_mfma_f32_16x16x32_bf16 v[124:127], v[128:131], v[188:191], v[124:127]
	v_mfma_f32_16x16x32_bf16 v[120:123], v[136:139], v[188:191], v[120:123]
	v_mfma_f32_16x16x32_bf16 v[108:111], v[128:131], v[196:199], v[108:111]
	v_mfma_f32_16x16x32_bf16 v[104:107], v[136:139], v[196:199], v[104:107]
	v_mfma_f32_16x16x32_bf16 v[92:95], v[128:131], v[204:207], v[92:95]
	v_mfma_f32_16x16x32_bf16 v[88:91], v[136:139], v[204:207], v[88:91]
	v_mfma_f32_16x16x32_bf16 v[76:79], v[128:131], v[212:215], v[76:79]
	v_mfma_f32_16x16x32_bf16 v[72:75], v[136:139], v[212:215], v[72:75]
	v_mfma_f32_16x16x32_bf16 v[124:127], v[132:135], v[192:195], v[124:127]
	v_mfma_f32_16x16x32_bf16 v[120:123], v[140:143], v[192:195], v[120:123]
	v_mfma_f32_16x16x32_bf16 v[108:111], v[132:135], v[200:203], v[108:111]
	v_mfma_f32_16x16x32_bf16 v[104:107], v[140:143], v[200:203], v[104:107]
	v_mfma_f32_16x16x32_bf16 v[92:95], v[132:135], v[208:211], v[92:95]
	v_mfma_f32_16x16x32_bf16 v[88:91], v[140:143], v[208:211], v[88:91]
	v_mfma_f32_16x16x32_bf16 v[76:79], v[132:135], v[216:219], v[76:79]
	v_mfma_f32_16x16x32_bf16 v[72:75], v[140:143], v[216:219], v[72:75]
	s_setprio 0
	s_setprio 1
	v_mfma_f32_16x16x32_bf16 v[116:119], v[166:169], v[188:191], v[116:119]
	v_mfma_f32_16x16x32_bf16 v[112:115], v[180:183], v[188:191], v[112:115]
	v_mfma_f32_16x16x32_bf16 v[100:103], v[166:169], v[196:199], v[100:103]
	v_mfma_f32_16x16x32_bf16 v[96:99], v[180:183], v[196:199], v[96:99]
	v_mfma_f32_16x16x32_bf16 v[84:87], v[166:169], v[204:207], v[84:87]
	v_mfma_f32_16x16x32_bf16 v[80:83], v[180:183], v[204:207], v[80:83]
	v_mfma_f32_16x16x32_bf16 v[68:71], v[166:169], v[212:215], v[68:71]
	v_mfma_f32_16x16x32_bf16 v[64:67], v[180:183], v[212:215], v[64:67]
	v_mfma_f32_16x16x32_bf16 v[116:119], v[176:179], v[192:195], v[116:119]
	v_mfma_f32_16x16x32_bf16 v[112:115], v[184:187], v[192:195], v[112:115]
	v_mfma_f32_16x16x32_bf16 v[100:103], v[176:179], v[200:203], v[100:103]
	v_mfma_f32_16x16x32_bf16 v[96:99], v[184:187], v[200:203], v[96:99]
	v_mfma_f32_16x16x32_bf16 v[84:87], v[176:179], v[208:211], v[84:87]
	v_mfma_f32_16x16x32_bf16 v[80:83], v[184:187], v[208:211], v[80:83]
	v_mfma_f32_16x16x32_bf16 v[68:71], v[176:179], v[216:219], v[68:71]
	v_mfma_f32_16x16x32_bf16 v[64:67], v[184:187], v[216:219], v[64:67]
	s_setprio 0
	s_barrier
	s_add_i32 s2, s82, s36
	v_lshl_add_u64 v[170:171], v[170:171], 0, s[30:31]
	s_mov_b32 m0, s2
	ds_read_b128 v[188:191], v242 offset:49152
	ds_read_b128 v[192:195], v242 offset:50176
	ds_read_b128 v[196:199], v242 offset:51200
	ds_read_b128 v[200:203], v242 offset:52224
	ds_read_b128 v[204:207], v242 offset:53248
	ds_read_b128 v[208:211], v242 offset:54272
	ds_read_b128 v[212:215], v242 offset:55296
	ds_read_b128 v[216:219], v242 offset:56320
	global_load_lds_dwordx4 v[170:171], off
	v_lshl_add_u64 v[170:171], v[232:233], 0, s[30:31]
	s_add_i32 m0, s2, 0x2000
	s_add_i32 s2, s83, s36
	global_load_lds_dwordx4 v[170:171], off
	v_lshl_add_u64 v[170:171], v[234:235], 0, s[30:31]
	s_mov_b32 m0, s2
	s_nop 0
	global_load_lds_dwordx4 v[170:171], off
	v_lshl_add_u64 v[170:171], v[246:247], 0, s[30:31]
	s_add_i32 m0, s2, 0x2000
	s_nop 0
	global_load_lds_dwordx4 v[170:171], off
	v_lshl_add_u64 v[170:171], v[248:249], 0, s[30:31]
	s_mov_b32 m0, s63
	s_nop 0
	global_load_lds_dwordx4 v[170:171], off
	v_lshl_add_u64 v[170:171], v[250:251], 0, s[30:31]
	s_mov_b32 m0, s18
	s_nop 0
	global_load_lds_dwordx4 v[170:171], off
	s_waitcnt vmcnt(8) lgkmcnt(0)
	s_barrier
	s_setprio 1
	v_mfma_f32_16x16x32_bf16 v[60:63], v[128:131], v[188:191], v[60:63]
	v_mfma_f32_16x16x32_bf16 v[56:59], v[136:139], v[188:191], v[56:59]
	v_mfma_f32_16x16x32_bf16 v[44:47], v[128:131], v[196:199], v[44:47]
	v_mfma_f32_16x16x32_bf16 v[40:43], v[136:139], v[196:199], v[40:43]
	v_mfma_f32_16x16x32_bf16 v[28:31], v[128:131], v[204:207], v[28:31]
	v_mfma_f32_16x16x32_bf16 v[24:27], v[136:139], v[204:207], v[24:27]
	v_mfma_f32_16x16x32_bf16 v[12:15], v[128:131], v[212:215], v[12:15]
	v_mfma_f32_16x16x32_bf16 v[8:11], v[136:139], v[212:215], v[8:11]
	v_mfma_f32_16x16x32_bf16 v[60:63], v[132:135], v[192:195], v[60:63]
	v_mfma_f32_16x16x32_bf16 v[56:59], v[140:143], v[192:195], v[56:59]
	v_mfma_f32_16x16x32_bf16 v[44:47], v[132:135], v[200:203], v[44:47]
	v_mfma_f32_16x16x32_bf16 v[40:43], v[140:143], v[200:203], v[40:43]
	v_mfma_f32_16x16x32_bf16 v[28:31], v[132:135], v[208:211], v[28:31]
	v_mfma_f32_16x16x32_bf16 v[24:27], v[140:143], v[208:211], v[24:27]
	v_mfma_f32_16x16x32_bf16 v[12:15], v[132:135], v[216:219], v[12:15]
	v_mfma_f32_16x16x32_bf16 v[8:11], v[140:143], v[216:219], v[8:11]
	s_setprio 0
	s_setprio 1
	v_mfma_f32_16x16x32_bf16 v[52:55], v[166:169], v[188:191], v[52:55]
	v_mfma_f32_16x16x32_bf16 v[48:51], v[180:183], v[188:191], v[48:51]
	v_mfma_f32_16x16x32_bf16 v[36:39], v[166:169], v[196:199], v[36:39]
	v_mfma_f32_16x16x32_bf16 v[32:35], v[180:183], v[196:199], v[32:35]
	v_mfma_f32_16x16x32_bf16 v[20:23], v[166:169], v[204:207], v[20:23]
	v_mfma_f32_16x16x32_bf16 v[16:19], v[180:183], v[204:207], v[16:19]
	v_mfma_f32_16x16x32_bf16 v[4:7], v[166:169], v[212:215], v[4:7]
	v_mfma_f32_16x16x32_bf16 v[0:3], v[180:183], v[212:215], v[0:3]
	v_mfma_f32_16x16x32_bf16 v[52:55], v[176:179], v[192:195], v[52:55]
	v_mfma_f32_16x16x32_bf16 v[48:51], v[184:187], v[192:195], v[48:51]
	v_mfma_f32_16x16x32_bf16 v[36:39], v[176:179], v[200:203], v[36:39]
	v_mfma_f32_16x16x32_bf16 v[32:35], v[184:187], v[200:203], v[32:35]
	v_mfma_f32_16x16x32_bf16 v[20:23], v[176:179], v[208:211], v[20:23]
	v_mfma_f32_16x16x32_bf16 v[16:19], v[184:187], v[208:211], v[16:19]
	v_mfma_f32_16x16x32_bf16 v[4:7], v[176:179], v[216:219], v[4:7]
	v_mfma_f32_16x16x32_bf16 v[0:3], v[184:187], v[216:219], v[0:3]
	s_setprio 0
	s_barrier
	s_add_u32 s0, s0, 0x100
	s_addc_u32 s1, s1, 0
	s_add_u32 s11, s11, 0x100
	s_addc_u32 s24, s24, 0
	s_cmp_ge_u32 s90, s60
	s_mov_b32 s2, s90
	s_cbranch_scc1 .LBB0_297
.LBB0_295:
	s_add_i32 s90, s2, 2
	s_add_u32 s82, s0, 0x80
	s_addc_u32 s3, s1, 0
	s_add_i32 s83, 0, 0x10000
	s_cmp_eq_u32 s62, s2
	s_cselect_b32 s3, s23, s3
	s_cselect_b32 s2, s22, s82
	s_cselect_b32 vcc_hi, s13, s24
	s_cselect_b32 vcc_lo, s12, s11
	s_add_i32 s82, 0, 0x14000
	v_add_u32_e32 v140, s83, v157
	v_add_u32_e32 v144, s82, v157
	ds_read_b128 v[128:131], v140
	ds_read_b128 v[132:135], v140 offset:1024
	ds_read_b128 v[136:139], v140 offset:2048
	ds_read_b128 v[140:143], v140 offset:3072
	ds_read_b128 v[166:169], v144
	ds_read_b128 v[176:179], v144 offset:1024
	ds_read_b128 v[180:183], v144 offset:2048
	ds_read_b128 v[184:187], v144 offset:3072
	v_lshl_add_u64 v[170:171], s[0:1], 0, v[160:161]
	s_add_i32 m0, s37, 0xc000
	ds_read_b128 v[188:191], v242
	ds_read_b128 v[192:195], v242 offset:1024
	ds_read_b128 v[196:199], v242 offset:2048
	ds_read_b128 v[200:203], v242 offset:3072
	ds_read_b128 v[204:207], v242 offset:4096
	ds_read_b128 v[208:211], v242 offset:5120
	ds_read_b128 v[212:215], v242 offset:6144
	ds_read_b128 v[216:219], v242 offset:7168
	global_load_lds_dwordx4 v[170:171], off
	v_lshl_add_u64 v[170:171], s[0:1], 0, v[162:163]
	s_add_i32 m0, s37, 0xe000
	s_nop 0
	global_load_lds_dwordx4 v[170:171], off
	s_waitcnt vmcnt(8) lgkmcnt(0)
	s_barrier
	s_setprio 1
	v_mfma_f32_16x16x32_bf16 v[124:127], v[128:131], v[188:191], v[124:127]
	v_mfma_f32_16x16x32_bf16 v[120:123], v[136:139], v[188:191], v[120:123]
	v_mfma_f32_16x16x32_bf16 v[108:111], v[128:131], v[196:199], v[108:111]
	v_mfma_f32_16x16x32_bf16 v[104:107], v[136:139], v[196:199], v[104:107]
	v_mfma_f32_16x16x32_bf16 v[92:95], v[128:131], v[204:207], v[92:95]
	v_mfma_f32_16x16x32_bf16 v[88:91], v[136:139], v[204:207], v[88:91]
	v_mfma_f32_16x16x32_bf16 v[76:79], v[128:131], v[212:215], v[76:79]
	v_mfma_f32_16x16x32_bf16 v[72:75], v[136:139], v[212:215], v[72:75]
	v_mfma_f32_16x16x32_bf16 v[124:127], v[132:135], v[192:195], v[124:127]
	v_mfma_f32_16x16x32_bf16 v[120:123], v[140:143], v[192:195], v[120:123]
	v_mfma_f32_16x16x32_bf16 v[108:111], v[132:135], v[200:203], v[108:111]
	v_mfma_f32_16x16x32_bf16 v[104:107], v[140:143], v[200:203], v[104:107]
	v_mfma_f32_16x16x32_bf16 v[92:95], v[132:135], v[208:211], v[92:95]
	v_mfma_f32_16x16x32_bf16 v[88:91], v[140:143], v[208:211], v[88:91]
	v_mfma_f32_16x16x32_bf16 v[76:79], v[132:135], v[216:219], v[76:79]
	v_mfma_f32_16x16x32_bf16 v[72:75], v[140:143], v[216:219], v[72:75]
	s_setprio 0
	s_setprio 1
	v_mfma_f32_16x16x32_bf16 v[116:119], v[166:169], v[188:191], v[116:119]
	v_mfma_f32_16x16x32_bf16 v[112:115], v[180:183], v[188:191], v[112:115]
	v_mfma_f32_16x16x32_bf16 v[100:103], v[166:169], v[196:199], v[100:103]
	v_mfma_f32_16x16x32_bf16 v[96:99], v[180:183], v[196:199], v[96:99]
	v_mfma_f32_16x16x32_bf16 v[84:87], v[166:169], v[204:207], v[84:87]
	v_mfma_f32_16x16x32_bf16 v[80:83], v[180:183], v[204:207], v[80:83]
	v_mfma_f32_16x16x32_bf16 v[68:71], v[166:169], v[212:215], v[68:71]
	v_mfma_f32_16x16x32_bf16 v[64:67], v[180:183], v[212:215], v[64:67]
	v_mfma_f32_16x16x32_bf16 v[116:119], v[176:179], v[192:195], v[116:119]
	v_mfma_f32_16x16x32_bf16 v[112:115], v[184:187], v[192:195], v[112:115]
	v_mfma_f32_16x16x32_bf16 v[100:103], v[176:179], v[200:203], v[100:103]
	v_mfma_f32_16x16x32_bf16 v[96:99], v[184:187], v[200:203], v[96:99]
	v_mfma_f32_16x16x32_bf16 v[84:87], v[176:179], v[208:211], v[84:87]
	v_mfma_f32_16x16x32_bf16 v[80:83], v[184:187], v[208:211], v[80:83]
	v_mfma_f32_16x16x32_bf16 v[68:71], v[176:179], v[216:219], v[68:71]
	v_mfma_f32_16x16x32_bf16 v[64:67], v[184:187], v[216:219], v[64:67]
	s_setprio 0
	s_barrier
	s_add_i32 s83, s83, s36
	v_lshl_add_u64 v[170:171], vcc, 0, v[150:151]
	s_mov_b32 m0, s83
	ds_read_b128 v[188:191], v242 offset:16384
	ds_read_b128 v[192:195], v242 offset:17408
	ds_read_b128 v[196:199], v242 offset:18432
	ds_read_b128 v[200:203], v242 offset:19456
	ds_read_b128 v[204:207], v242 offset:20480
	ds_read_b128 v[208:211], v242 offset:21504
	ds_read_b128 v[212:215], v242 offset:22528
	ds_read_b128 v[216:219], v242 offset:23552
	global_load_lds_dwordx4 v[170:171], off
	s_add_i32 m0, s83, 0x2000
	v_lshl_add_u64 v[232:233], vcc, 0, v[154:155]
	s_add_u32 vcc_lo, vcc_lo, s26
	s_addc_u32 vcc_hi, vcc_hi, 0
	s_add_i32 s82, s82, s36
	global_load_lds_dwordx4 v[232:233], off
	v_lshl_add_u64 v[234:235], vcc, 0, v[150:151]
	s_mov_b32 m0, s82
	v_lshl_add_u64 v[246:247], vcc, 0, v[154:155]
	global_load_lds_dwordx4 v[234:235], off
	s_add_i32 m0, s82, 0x2000
	v_lshl_add_u64 v[248:249], s[2:3], 0, v[148:149]
	global_load_lds_dwordx4 v[246:247], off
	s_mov_b32 m0, s37
	v_lshl_add_u64 v[250:251], s[2:3], 0, v[152:153]
	global_load_lds_dwordx4 v[248:249], off
	s_mov_b32 m0, s42
	s_nop 0
	global_load_lds_dwordx4 v[250:251], off
	s_waitcnt vmcnt(8) lgkmcnt(0)
	s_barrier
	s_setprio 1
	v_mfma_f32_16x16x32_bf16 v[60:63], v[128:131], v[188:191], v[60:63]
	v_mfma_f32_16x16x32_bf16 v[56:59], v[136:139], v[188:191], v[56:59]
	v_mfma_f32_16x16x32_bf16 v[44:47], v[128:131], v[196:199], v[44:47]
	v_mfma_f32_16x16x32_bf16 v[40:43], v[136:139], v[196:199], v[40:43]
	v_mfma_f32_16x16x32_bf16 v[28:31], v[128:131], v[204:207], v[28:31]
	v_mfma_f32_16x16x32_bf16 v[24:27], v[136:139], v[204:207], v[24:27]
	v_mfma_f32_16x16x32_bf16 v[12:15], v[128:131], v[212:215], v[12:15]
	v_mfma_f32_16x16x32_bf16 v[8:11], v[136:139], v[212:215], v[8:11]
	v_mfma_f32_16x16x32_bf16 v[60:63], v[132:135], v[192:195], v[60:63]
	v_mfma_f32_16x16x32_bf16 v[56:59], v[140:143], v[192:195], v[56:59]
	v_mfma_f32_16x16x32_bf16 v[44:47], v[132:135], v[200:203], v[44:47]
	v_mfma_f32_16x16x32_bf16 v[40:43], v[140:143], v[200:203], v[40:43]
	v_mfma_f32_16x16x32_bf16 v[28:31], v[132:135], v[208:211], v[28:31]
	v_mfma_f32_16x16x32_bf16 v[24:27], v[140:143], v[208:211], v[24:27]
	v_mfma_f32_16x16x32_bf16 v[12:15], v[132:135], v[216:219], v[12:15]
	v_mfma_f32_16x16x32_bf16 v[8:11], v[140:143], v[216:219], v[8:11]
	s_setprio 0
	s_setprio 1
	v_mfma_f32_16x16x32_bf16 v[52:55], v[166:169], v[188:191], v[52:55]
	v_mfma_f32_16x16x32_bf16 v[48:51], v[180:183], v[188:191], v[48:51]
	v_mfma_f32_16x16x32_bf16 v[36:39], v[166:169], v[196:199], v[36:39]
	v_mfma_f32_16x16x32_bf16 v[32:35], v[180:183], v[196:199], v[32:35]
	v_mfma_f32_16x16x32_bf16 v[20:23], v[166:169], v[204:207], v[20:23]
	v_mfma_f32_16x16x32_bf16 v[16:19], v[180:183], v[204:207], v[16:19]
	v_mfma_f32_16x16x32_bf16 v[4:7], v[166:169], v[212:215], v[4:7]
	v_mfma_f32_16x16x32_bf16 v[0:3], v[180:183], v[212:215], v[0:3]
	v_mfma_f32_16x16x32_bf16 v[52:55], v[176:179], v[192:195], v[52:55]
	v_mfma_f32_16x16x32_bf16 v[48:51], v[184:187], v[192:195], v[48:51]
	v_mfma_f32_16x16x32_bf16 v[36:39], v[176:179], v[200:203], v[36:39]
	v_mfma_f32_16x16x32_bf16 v[32:35], v[184:187], v[200:203], v[32:35]
	v_mfma_f32_16x16x32_bf16 v[20:23], v[176:179], v[208:211], v[20:23]
	v_mfma_f32_16x16x32_bf16 v[16:19], v[184:187], v[208:211], v[16:19]
	v_mfma_f32_16x16x32_bf16 v[4:7], v[176:179], v[216:219], v[4:7]
	v_mfma_f32_16x16x32_bf16 v[0:3], v[184:187], v[216:219], v[0:3]
	s_setprio 0
	s_barrier
	s_add_i32 s82, 0, 0x18000
	s_add_i32 s83, 0, 0x1c000
	v_add_u32_e32 v140, s82, v157
	v_add_u32_e32 v144, s83, v157
	ds_read_b128 v[128:131], v140
	ds_read_b128 v[132:135], v140 offset:1024
	ds_read_b128 v[136:139], v140 offset:2048
	ds_read_b128 v[140:143], v140 offset:3072
	ds_read_b128 v[166:169], v144
	ds_read_b128 v[176:179], v144 offset:1024
	ds_read_b128 v[180:183], v144 offset:2048
	ds_read_b128 v[184:187], v144 offset:3072
	s_add_u32 s2, s2, s58
	s_addc_u32 s3, s3, 0
	s_mov_b32 m0, s43
	v_lshl_add_u64 v[238:239], s[2:3], 0, v[148:149]
	ds_read_b128 v[188:191], v242 offset:32768
	ds_read_b128 v[192:195], v242 offset:33792
	ds_read_b128 v[196:199], v242 offset:34816
	ds_read_b128 v[200:203], v242 offset:35840
	ds_read_b128 v[204:207], v242 offset:36864
	ds_read_b128 v[208:211], v242 offset:37888
	ds_read_b128 v[212:215], v242 offset:38912
	ds_read_b128 v[216:219], v242 offset:39936
	global_load_lds_dwordx4 v[238:239], off
	v_lshl_add_u64 v[238:239], s[2:3], 0, v[152:153]
	s_mov_b32 m0, s16
	s_nop 0
	global_load_lds_dwordx4 v[238:239], off
	s_waitcnt vmcnt(8) lgkmcnt(0)
	s_barrier
	s_setprio 1
	v_mfma_f32_16x16x32_bf16 v[124:127], v[128:131], v[188:191], v[124:127]
	v_mfma_f32_16x16x32_bf16 v[120:123], v[136:139], v[188:191], v[120:123]
	v_mfma_f32_16x16x32_bf16 v[108:111], v[128:131], v[196:199], v[108:111]
	v_mfma_f32_16x16x32_bf16 v[104:107], v[136:139], v[196:199], v[104:107]
	v_mfma_f32_16x16x32_bf16 v[92:95], v[128:131], v[204:207], v[92:95]
	v_mfma_f32_16x16x32_bf16 v[88:91], v[136:139], v[204:207], v[88:91]
	v_mfma_f32_16x16x32_bf16 v[76:79], v[128:131], v[212:215], v[76:79]
	v_mfma_f32_16x16x32_bf16 v[72:75], v[136:139], v[212:215], v[72:75]
	v_mfma_f32_16x16x32_bf16 v[124:127], v[132:135], v[192:195], v[124:127]
	v_mfma_f32_16x16x32_bf16 v[120:123], v[140:143], v[192:195], v[120:123]
	v_mfma_f32_16x16x32_bf16 v[108:111], v[132:135], v[200:203], v[108:111]
	v_mfma_f32_16x16x32_bf16 v[104:107], v[140:143], v[200:203], v[104:107]
	v_mfma_f32_16x16x32_bf16 v[92:95], v[132:135], v[208:211], v[92:95]
	v_mfma_f32_16x16x32_bf16 v[88:91], v[140:143], v[208:211], v[88:91]
	v_mfma_f32_16x16x32_bf16 v[76:79], v[132:135], v[216:219], v[76:79]
	v_mfma_f32_16x16x32_bf16 v[72:75], v[140:143], v[216:219], v[72:75]
	s_setprio 0
	s_setprio 1
	v_mfma_f32_16x16x32_bf16 v[116:119], v[166:169], v[188:191], v[116:119]
	v_mfma_f32_16x16x32_bf16 v[112:115], v[180:183], v[188:191], v[112:115]
	v_mfma_f32_16x16x32_bf16 v[100:103], v[166:169], v[196:199], v[100:103]
	v_mfma_f32_16x16x32_bf16 v[96:99], v[180:183], v[196:199], v[96:99]
	v_mfma_f32_16x16x32_bf16 v[84:87], v[166:169], v[204:207], v[84:87]
	v_mfma_f32_16x16x32_bf16 v[80:83], v[180:183], v[204:207], v[80:83]
	v_mfma_f32_16x16x32_bf16 v[68:71], v[166:169], v[212:215], v[68:71]
	v_mfma_f32_16x16x32_bf16 v[64:67], v[180:183], v[212:215], v[64:67]
	v_mfma_f32_16x16x32_bf16 v[116:119], v[176:179], v[192:195], v[116:119]
	v_mfma_f32_16x16x32_bf16 v[112:115], v[184:187], v[192:195], v[112:115]
	v_mfma_f32_16x16x32_bf16 v[100:103], v[176:179], v[200:203], v[100:103]
	v_mfma_f32_16x16x32_bf16 v[96:99], v[184:187], v[200:203], v[96:99]
	v_mfma_f32_16x16x32_bf16 v[84:87], v[176:179], v[208:211], v[84:87]
	v_mfma_f32_16x16x32_bf16 v[80:83], v[184:187], v[208:211], v[80:83]
	v_mfma_f32_16x16x32_bf16 v[68:71], v[176:179], v[216:219], v[68:71]
	v_mfma_f32_16x16x32_bf16 v[64:67], v[184:187], v[216:219], v[64:67]
	s_setprio 0
	s_barrier
	s_add_i32 s2, s82, s36
	v_lshl_add_u64 v[170:171], v[170:171], 0, s[30:31]
	s_mov_b32 m0, s2
	ds_read_b128 v[188:191], v242 offset:49152
	ds_read_b128 v[192:195], v242 offset:50176
	ds_read_b128 v[196:199], v242 offset:51200
	ds_read_b128 v[200:203], v242 offset:52224
	ds_read_b128 v[204:207], v242 offset:53248
	ds_read_b128 v[208:211], v242 offset:54272
	ds_read_b128 v[212:215], v242 offset:55296
	ds_read_b128 v[216:219], v242 offset:56320
	global_load_lds_dwordx4 v[170:171], off
	v_lshl_add_u64 v[170:171], v[232:233], 0, s[30:31]
	s_add_i32 m0, s2, 0x2000
	s_add_i32 s2, s83, s36
	global_load_lds_dwordx4 v[170:171], off
	v_lshl_add_u64 v[170:171], v[234:235], 0, s[30:31]
	s_mov_b32 m0, s2
	s_nop 0
	global_load_lds_dwordx4 v[170:171], off
	v_lshl_add_u64 v[170:171], v[246:247], 0, s[30:31]
	s_add_i32 m0, s2, 0x2000
	s_nop 0
	global_load_lds_dwordx4 v[170:171], off
	v_lshl_add_u64 v[170:171], v[248:249], 0, s[30:31]
	s_mov_b32 m0, s63
	s_nop 0
	global_load_lds_dwordx4 v[170:171], off
	v_lshl_add_u64 v[170:171], v[250:251], 0, s[30:31]
	s_mov_b32 m0, s18
	s_nop 0
	global_load_lds_dwordx4 v[170:171], off
	s_waitcnt vmcnt(8) lgkmcnt(0)
	s_barrier
	s_setprio 1
	v_mfma_f32_16x16x32_bf16 v[60:63], v[128:131], v[188:191], v[60:63]
	v_mfma_f32_16x16x32_bf16 v[56:59], v[136:139], v[188:191], v[56:59]
	v_mfma_f32_16x16x32_bf16 v[44:47], v[128:131], v[196:199], v[44:47]
	v_mfma_f32_16x16x32_bf16 v[40:43], v[136:139], v[196:199], v[40:43]
	v_mfma_f32_16x16x32_bf16 v[28:31], v[128:131], v[204:207], v[28:31]
	v_mfma_f32_16x16x32_bf16 v[24:27], v[136:139], v[204:207], v[24:27]
	v_mfma_f32_16x16x32_bf16 v[12:15], v[128:131], v[212:215], v[12:15]
	v_mfma_f32_16x16x32_bf16 v[8:11], v[136:139], v[212:215], v[8:11]
	v_mfma_f32_16x16x32_bf16 v[60:63], v[132:135], v[192:195], v[60:63]
	v_mfma_f32_16x16x32_bf16 v[56:59], v[140:143], v[192:195], v[56:59]
	v_mfma_f32_16x16x32_bf16 v[44:47], v[132:135], v[200:203], v[44:47]
	v_mfma_f32_16x16x32_bf16 v[40:43], v[140:143], v[200:203], v[40:43]
	v_mfma_f32_16x16x32_bf16 v[28:31], v[132:135], v[208:211], v[28:31]
	v_mfma_f32_16x16x32_bf16 v[24:27], v[140:143], v[208:211], v[24:27]
	v_mfma_f32_16x16x32_bf16 v[12:15], v[132:135], v[216:219], v[12:15]
	v_mfma_f32_16x16x32_bf16 v[8:11], v[140:143], v[216:219], v[8:11]
	s_setprio 0
	s_setprio 1
	v_mfma_f32_16x16x32_bf16 v[52:55], v[166:169], v[188:191], v[52:55]
	v_mfma_f32_16x16x32_bf16 v[48:51], v[180:183], v[188:191], v[48:51]
	v_mfma_f32_16x16x32_bf16 v[36:39], v[166:169], v[196:199], v[36:39]
	v_mfma_f32_16x16x32_bf16 v[32:35], v[180:183], v[196:199], v[32:35]
	v_mfma_f32_16x16x32_bf16 v[20:23], v[166:169], v[204:207], v[20:23]
	v_mfma_f32_16x16x32_bf16 v[16:19], v[180:183], v[204:207], v[16:19]
	v_mfma_f32_16x16x32_bf16 v[4:7], v[166:169], v[212:215], v[4:7]
	v_mfma_f32_16x16x32_bf16 v[0:3], v[180:183], v[212:215], v[0:3]
	v_mfma_f32_16x16x32_bf16 v[52:55], v[176:179], v[192:195], v[52:55]
	v_mfma_f32_16x16x32_bf16 v[48:51], v[184:187], v[192:195], v[48:51]
	v_mfma_f32_16x16x32_bf16 v[36:39], v[176:179], v[200:203], v[36:39]
	v_mfma_f32_16x16x32_bf16 v[32:35], v[184:187], v[200:203], v[32:35]
	v_mfma_f32_16x16x32_bf16 v[20:23], v[176:179], v[208:211], v[20:23]
	v_mfma_f32_16x16x32_bf16 v[16:19], v[184:187], v[208:211], v[16:19]
	v_mfma_f32_16x16x32_bf16 v[4:7], v[176:179], v[216:219], v[4:7]
	v_mfma_f32_16x16x32_bf16 v[0:3], v[184:187], v[216:219], v[0:3]
	s_setprio 0
	s_barrier
	s_add_u32 s0, s0, 0x100
	s_addc_u32 s1, s1, 0
	s_add_u32 s11, s11, 0x100
	s_addc_u32 s24, s24, 0
	s_cmp_ge_u32 s90, s60
	s_mov_b32 s2, s90
	s_cbranch_scc0 .LBB0_295
	s_branch .LBB0_297
